# s5_pass2 B.u products on f32 MFMA too (BU via LDS in 8-token halves, next block MFMAs interleaved with second-half steps)
# speedup vs baseline: 1.0157x; 1.0013x over previous
.LBB0_1049:
	v_pk_mul_f32 v[82:83], v[78:79], v[78:79]
	v_xor_b32_e32 v79, 0x80000000, v79
	v_add_f32_e32 v68, v82, v83
	v_div_scale_f32 v73, s[8:9], v68, v68, 1.0
	v_rcp_f32_e32 v75, v73
	v_div_scale_f32 v82, vcc, 1.0, v68, 1.0
	s_waitcnt vmcnt(7)
	v_bfe_u32 v86, v62, 16, 1
	v_fma_f32 v83, -v73, v75, 1.0
	v_fmac_f32_e32 v75, v83, v75
	v_mul_f32_e32 v83, v82, v75
	v_fma_f32 v84, -v73, v83, v82
	v_fmac_f32_e32 v83, v84, v75
	v_fma_f32 v73, -v73, v83, v82
	v_div_fmas_f32 v73, v73, v75, v83
	v_div_fixup_f32 v68, v73, v68, 1.0
	v_add_f32_e32 v82, -1.0, v72
	v_pk_mul_f32 v[78:79], v[78:79], v[68:69] op_sel_hi:[1,0]
	v_mov_b32_e32 v83, v74
	v_mov_b32_e32 v75, v82
	v_pk_mul_f32 v[84:85], v[78:79], v[82:83]
	v_pk_mul_f32 v[78:79], v[78:79], v[74:75]
	v_bfe_u32 v68, v59, 16, 1
	v_bfe_u32 v73, v58, 16, 1
	v_bfe_u32 v75, v57, 16, 1
	v_bfe_u32 v82, v56, 16, 1
	v_add3_u32 v110, v56, v82, s77
	v_add3_u32 v75, v57, v75, s77
	v_add3_u32 v73, v58, v73, s77
	v_add3_u32 v68, v59, v68, s77
	s_waitcnt vmcnt(6)
	v_bfe_u32 v56, v43, 16, 1
	v_bfe_u32 v57, v42, 16, 1
	v_bfe_u32 v58, v41, 16, 1
	v_bfe_u32 v59, v40, 16, 1
	v_bfe_u32 v83, v63, 16, 1
	v_bfe_u32 v87, v61, 16, 1
	v_bfe_u32 v88, v60, 16, 1
	v_add3_u32 v115, v40, v59, s77
	v_add3_u32 v116, v41, v58, s77
	v_add3_u32 v117, v42, v57, s77
	v_add3_u32 v118, v43, v56, s77
	s_waitcnt vmcnt(3)
	v_xor_b32_e32 v40, 0x80000000, v52
	v_xor_b32_e32 v41, 0x80000000, v53
	v_xor_b32_e32 v42, 0x80000000, v54
	v_xor_b32_e32 v43, 0x80000000, v55
	v_add3_u32 v106, v60, v88, s77
	v_add3_u32 v107, v61, v87, s77
	v_add3_u32 v108, v62, v86, s77
	v_add3_u32 v109, v63, v83, s77
	v_bfe_u32 v60, v51, 16, 1
	v_bfe_u32 v61, v50, 16, 1
	v_bfe_u32 v62, v49, 16, 1
	v_bfe_u32 v63, v48, 16, 1
	v_xor_b32_e32 v44, 0x80000000, v44
	v_xor_b32_e32 v45, 0x80000000, v45
	v_xor_b32_e32 v46, 0x80000000, v46
	v_xor_b32_e32 v47, 0x80000000, v47
	v_bfe_u32 v52, v43, 16, 1
	v_bfe_u32 v53, v42, 16, 1
	v_bfe_u32 v54, v41, 16, 1
	v_bfe_u32 v55, v40, 16, 1
	s_waitcnt vmcnt(2)
	v_xor_b32_e32 v32, 0x80000000, v32
	v_xor_b32_e32 v33, 0x80000000, v33
	v_xor_b32_e32 v34, 0x80000000, v34
	v_xor_b32_e32 v35, 0x80000000, v35
	v_add3_u32 v111, v48, v63, s77
	v_add3_u32 v112, v49, v62, s77
	v_add3_u32 v113, v50, v61, s77
	v_add3_u32 v114, v51, v60, s77
	v_bfe_u32 v48, v47, 16, 1
	v_bfe_u32 v49, v46, 16, 1
	v_bfe_u32 v50, v45, 16, 1
	v_bfe_u32 v51, v44, 16, 1
	v_add3_u32 v119, v40, v55, s77
	v_add3_u32 v130, v41, v54, s77
	v_add3_u32 v131, v42, v53, s77
	v_add3_u32 v132, v43, v52, s77
	s_waitcnt vmcnt(1)
	v_xor_b32_e32 v36, 0x80000000, v36
	v_xor_b32_e32 v37, 0x80000000, v37
	v_xor_b32_e32 v38, 0x80000000, v38
	v_xor_b32_e32 v39, 0x80000000, v39
	v_bfe_u32 v40, v35, 16, 1
	v_bfe_u32 v41, v34, 16, 1
	v_bfe_u32 v42, v33, 16, 1
	v_bfe_u32 v43, v32, 16, 1
	v_add3_u32 v133, v44, v51, s77
	v_add3_u32 v134, v45, v50, s77
	v_add3_u32 v135, v46, v49, s77
	v_add3_u32 v136, v47, v48, s77
	v_bfe_u32 v44, v39, 16, 1
	v_bfe_u32 v45, v38, 16, 1
	v_bfe_u32 v46, v37, 16, 1
	v_bfe_u32 v47, v36, 16, 1
	v_add3_u32 v141, v32, v43, s77
	v_add3_u32 v142, v33, v42, s77
	v_add3_u32 v143, v34, v41, s77
	v_add3_u32 v144, v35, v40, s77
	v_mov_b32_e32 v32, v20
	v_mov_b32_e32 v33, v24
	v_pk_add_f32 v[34:35], v[78:79], v[78:79] op_sel:[1,0] op_sel_hi:[1,0]
	v_mov_b32_e32 v91, v28
	v_mov_b32_e32 v92, v28
	v_mov_b32_e32 v28, v1
	v_add3_u32 v137, v36, v47, s77
	v_add3_u32 v138, v37, v46, s77
	v_add3_u32 v139, v38, v45, s77
	v_add3_u32 v140, v39, v44, s77
	v_pk_mul_f32 v[32:33], v[32:33], v[34:35]
	v_mov_b32_e32 v36, v24
	v_mov_b32_e32 v37, v20
	v_pk_add_f32 v[50:51], v[84:85], v[84:85] op_sel:[0,1] op_sel_hi:[0,1] neg_lo:[0,1] neg_hi:[0,1]
	v_mov_b32_e32 v38, v21
	v_mov_b32_e32 v39, v25
	v_pk_mul_f32 v[94:95], v[28:29], v[34:35]
	v_mov_b32_e32 v96, v29
	v_mov_b32_e32 v28, v2
	v_mov_b32_e32 v29, v30
	v_pk_mul_f32 v[38:39], v[38:39], v[34:35]
	v_mov_b32_e32 v20, v25
	v_mov_b32_e32 v40, v22
	v_mov_b32_e32 v41, v26
	v_pk_mul_f32 v[98:99], v[28:29], v[34:35]
	v_pk_fma_f32 v[24:25], v[24:25], v[50:51], v[32:33] neg_lo:[0,0,1] neg_hi:[0,0,1]
	v_pk_fma_f32 v[28:29], v[36:37], v[50:51], v[32:33]
	v_pk_mul_f32 v[40:41], v[40:41], v[34:35]
	v_mov_b32_e32 v42, v26
	v_mov_b32_e32 v43, v22
	v_mov_b32_e32 v44, v23
	v_mov_b32_e32 v45, v27
	v_mov_b32_e32 v78, v5
	v_mov_b32_e32 v79, v9
	v_mov_b32_e32 v25, v29
	v_pk_fma_f32 v[28:29], v[20:21], v[50:51], v[38:39] neg_lo:[0,0,1] neg_hi:[0,0,1]
	v_pk_fma_f32 v[20:21], v[20:21], v[50:51], v[38:39]
	v_pk_mul_f32 v[44:45], v[44:45], v[34:35]
	v_mov_b32_e32 v22, v27
	v_mov_b32_e32 v46, v12
	v_mov_b32_e32 v47, v16
	v_mov_b32_e32 v52, v13
	v_mov_b32_e32 v53, v17
	v_pk_mul_f32 v[78:79], v[78:79], v[34:35]
	v_mov_b32_e32 v82, v9
	v_mov_b32_e32 v83, v5
	v_mov_b32_e32 v84, v6
	v_mov_b32_e32 v85, v10
	v_mov_b32_e32 v29, v21
	v_pk_fma_f32 v[20:21], v[26:27], v[50:51], v[40:41] neg_lo:[0,0,1] neg_hi:[0,0,1]
	v_pk_fma_f32 v[26:27], v[42:43], v[50:51], v[40:41]
	v_pk_mul_f32 v[46:47], v[46:47], v[34:35]
	v_mov_b32_e32 v48, v16
	v_mov_b32_e32 v49, v12
	v_pk_mul_f32 v[52:53], v[52:53], v[34:35]
	v_mov_b32_e32 v12, v17
	v_mov_b32_e32 v54, v14
	v_mov_b32_e32 v55, v18
	v_mov_b32_e32 v60, v4
	v_mov_b32_e32 v63, v4
	v_pk_mul_f32 v[84:85], v[84:85], v[34:35]
	v_mov_b32_e32 v86, v10
	v_mov_b32_e32 v87, v6
	v_mov_b32_e32 v10, v7
	v_mov_b32_e32 v97, v1
	v_mov_b32_e32 v100, v30
	v_mov_b32_e32 v30, v3
	v_mov_b32_e32 v21, v27
	v_pk_fma_f32 v[26:27], v[22:23], v[50:51], v[44:45] neg_lo:[0,0,1] neg_hi:[0,0,1]
	v_pk_fma_f32 v[22:23], v[22:23], v[50:51], v[44:45]
	v_pk_fma_f32 v[4:5], v[4:5], v[50:51], v[78:79]
	v_pk_fma_f32 v[38:39], v[82:83], v[50:51], v[78:79] neg_lo:[0,0,1] neg_hi:[0,0,1]
	v_pk_mul_f32 v[54:55], v[54:55], v[34:35]
	v_mov_b32_e32 v56, v18
	v_mov_b32_e32 v57, v14
	v_mov_b32_e32 v58, v15
	v_mov_b32_e32 v59, v19
	v_mov_b32_e32 v61, v8
	v_pk_mul_f32 v[88:89], v[10:11], v[34:35]
	v_mov_b32_e32 v10, v11
	v_mov_b32_e32 v11, v7
	v_mov_b32_e32 v90, v0
	v_mov_b32_e32 v93, v0
	v_mov_b32_e32 v101, v2
	v_pk_mul_f32 v[102:103], v[30:31], v[34:35]
	v_mov_b32_e32 v104, v31
	v_mov_b32_e32 v27, v23
	v_pk_fma_f32 v[22:23], v[16:17], v[50:51], v[46:47] neg_lo:[0,0,1] neg_hi:[0,0,1]
	v_pk_fma_f32 v[16:17], v[48:49], v[50:51], v[46:47]
	v_pk_fma_f32 v[30:31], v[12:13], v[50:51], v[52:53] neg_lo:[0,0,1] neg_hi:[0,0,1]
	v_pk_fma_f32 v[12:13], v[12:13], v[50:51], v[52:53]
	v_mov_b32_e32 v39, v5
	v_pk_fma_f32 v[4:5], v[86:87], v[50:51], v[84:85]
	v_pk_fma_f32 v[40:41], v[86:87], v[50:51], v[84:85] neg_lo:[0,0,1] neg_hi:[0,0,1]
	v_pk_fma_f32 v[0:1], v[0:1], v[50:51], v[94:95]
	v_pk_fma_f32 v[46:47], v[96:97], v[50:51], v[94:95] neg_lo:[0,0,1] neg_hi:[0,0,1]
	v_pk_mul_f32 v[58:59], v[58:59], v[34:35]
	v_mov_b32_e32 v14, v19
	v_pk_mul_f32 v[60:61], v[60:61], v[34:35]
	v_mov_b32_e32 v62, v8
	v_pk_mul_f32 v[90:91], v[90:91], v[34:35]
	v_mov_b32_e32 v105, v3
	v_mov_b32_e32 v31, v13
	v_pk_fma_f32 v[32:33], v[18:19], v[50:51], v[54:55] neg_lo:[0,0,1] neg_hi:[0,0,1]
	v_pk_fma_f32 v[12:13], v[56:57], v[50:51], v[54:55]
	v_mov_b32_e32 v41, v5
	v_pk_fma_f32 v[4:5], v[6:7], v[50:51], v[88:89]
	v_pk_fma_f32 v[42:43], v[10:11], v[50:51], v[88:89] neg_lo:[0,0,1] neg_hi:[0,0,1]
	v_mov_b32_e32 v47, v1
	v_pk_fma_f32 v[0:1], v[100:101], v[50:51], v[98:99]
	v_pk_fma_f32 v[48:49], v[100:101], v[50:51], v[98:99] neg_lo:[0,0,1] neg_hi:[0,0,1]
	v_mov_b32_e32 v33, v13
	v_pk_fma_f32 v[34:35], v[14:15], v[50:51], v[58:59] neg_lo:[0,0,1] neg_hi:[0,0,1]
	v_pk_fma_f32 v[12:13], v[14:15], v[50:51], v[58:59]
	v_pk_fma_f32 v[36:37], v[8:9], v[50:51], v[60:61] neg_lo:[0,0,1] neg_hi:[0,0,1]
	v_pk_fma_f32 v[8:9], v[62:63], v[50:51], v[60:61]
	v_mov_b32_e32 v43, v5
	v_pk_fma_f32 v[4:5], v[92:93], v[50:51], v[90:91]
	v_pk_fma_f32 v[44:45], v[92:93], v[50:51], v[90:91] neg_lo:[0,0,1] neg_hi:[0,0,1]
	v_mov_b32_e32 v49, v1
	v_pk_fma_f32 v[0:1], v[2:3], v[50:51], v[102:103]
	v_pk_fma_f32 v[50:51], v[104:105], v[50:51], v[102:103] neg_lo:[0,0,1] neg_hi:[0,0,1]
	s_xor_b64 s[6:7], s[58:59], -1
	v_mov_b32_e32 v23, v17
	v_mov_b32_e32 v35, v13
	v_mov_b32_e32 v37, v9
	v_mov_b32_e32 v45, v5
	v_mov_b32_e32 v51, v1
	v_lshl_add_u32 v54, v80, 2, 0
	v_lshl_add_u64 v[52:53], v[80:81], 1, s[48:49]
	v_perm_b32 v3, v68, v73, s78
	v_perm_b32 v2, v75, v110, s78
	v_perm_b32 v1, v109, v108, s78
	v_perm_b32 v0, v107, v106, s78
	v_perm_b32 v7, v118, v117, s78
	v_perm_b32 v6, v116, v115, s78
	v_perm_b32 v5, v114, v113, s78
	v_perm_b32 v4, v112, v111, s78
	v_perm_b32 v11, v136, v135, s78
	v_perm_b32 v10, v134, v133, s78
	v_perm_b32 v9, v132, v131, s78
	v_perm_b32 v8, v130, v119, s78
	v_perm_b32 v15, v144, v143, s78
	v_perm_b32 v14, v142, v141, s78
	v_perm_b32 v13, v140, v139, s78
	v_perm_b32 v12, v138, v137, s78
	v_mov_b32_e32 v73, v72
	v_mov_b32_e32 v75, v74
	s_lshl_b32 s10, s56, 6
	s_mov_b32 s11, 0
	s_waitcnt vmcnt(0)
	v_mbcnt_lo_u32_b32 v155, -1, 0
	v_mbcnt_hi_u32_b32 v155, -1, v155
	s_mul_i32 s9, s63, 0x1600
	s_add_i32 s9, s9, 0x18800
	v_and_b32_e32 v196, 15, v155
	v_lshrrev_b32_e32 v197, 4, v155
	v_bfe_u32 v198, v155, 1, 3
	v_and_b32_e32 v200, 31, v155
	v_lshlrev_b32_e32 v200, 7, v200
	v_lshl_or_b32 v200, v198, 4, v200
	v_add_u32_e32 v200, s9, v200
	v_xor_b32_e32 v245, 16, v200
	v_xor_b32_e32 v246, 32, v200
	v_xor_b32_e32 v247, 48, v200
	v_xor_b32_e32 v248, 64, v200
	v_xor_b32_e32 v249, 80, v200
	v_xor_b32_e32 v250, 96, v200
	v_xor_b32_e32 v251, 112, v200
	v_bfe_u32 v198, v196, 1, 3
	v_lshlrev_b32_e32 v199, 1, v197
	v_xor_b32_e32 v199, v199, v198
	v_lshlrev_b32_e32 v201, 7, v196
	v_lshl_or_b32 v201, v199, 4, v201
	v_add_u32_e32 v201, s9, v201
	v_xor_b32_e32 v202, 16, v201
	s_mov_b32 exec_lo, -1
	s_mov_b32 exec_hi, 0
	ds_write_b64 v200, v[24:25]
	ds_write_b64 v200, v[28:29] offset:8
	ds_write_b64 v245, v[20:21]
	ds_write_b64 v245, v[26:27] offset:8
	ds_write_b64 v246, v[22:23]
	ds_write_b64 v246, v[30:31] offset:8
	ds_write_b64 v247, v[32:33]
	ds_write_b64 v247, v[34:35] offset:8
	ds_write_b64 v248, v[36:37]
	ds_write_b64 v248, v[38:39] offset:8
	ds_write_b64 v249, v[40:41]
	ds_write_b64 v249, v[42:43] offset:8
	ds_write_b64 v250, v[44:45]
	ds_write_b64 v250, v[46:47] offset:8
	ds_write_b64 v251, v[48:49]
	ds_write_b64 v251, v[50:51] offset:8
	s_mov_b64 exec, -1
	ds_read_b128 v[160:163], v201
	ds_read_b128 v[164:167], v202
	ds_read_b128 v[168:171], v201 offset:2048
	ds_read_b128 v[172:175], v202 offset:2048
	s_mov_b32 exec_lo, 0
	s_mov_b32 exec_hi, -1
	ds_write_b64 v200, v[24:25]
	ds_write_b64 v200, v[28:29] offset:8
	ds_write_b64 v245, v[20:21]
	ds_write_b64 v245, v[26:27] offset:8
	ds_write_b64 v246, v[22:23]
	ds_write_b64 v246, v[30:31] offset:8
	ds_write_b64 v247, v[32:33]
	ds_write_b64 v247, v[34:35] offset:8
	ds_write_b64 v248, v[36:37]
	ds_write_b64 v248, v[38:39] offset:8
	ds_write_b64 v249, v[40:41]
	ds_write_b64 v249, v[42:43] offset:8
	ds_write_b64 v250, v[44:45]
	ds_write_b64 v250, v[46:47] offset:8
	ds_write_b64 v251, v[48:49]
	ds_write_b64 v251, v[50:51] offset:8
	s_mov_b64 exec, -1
	ds_read_b128 v[176:179], v201
	ds_read_b128 v[180:183], v202
	ds_read_b128 v[184:187], v201 offset:2048
	ds_read_b128 v[188:191], v202 offset:2048
	v_lshlrev_b32_e32 v145, 10, v196
	v_lshl_add_u32 v145, v197, 4, v145
	v_and_b32_e32 v198, 1, v197
	v_lshlrev_b32_e32 v198, 11, v198
	v_lshl_add_u32 v198, v196, 2, v198
	v_add_u32_e32 v198, s9, v198
	v_mov_b32_e32 v199, v197
	v_lshl_add_u32 v146, v199, 6, v198
	v_xor_b32_e32 v199, 1, v197
	v_lshl_add_u32 v147, v199, 6, v198
	v_xor_b32_e32 v199, 2, v197
	v_lshl_add_u32 v148, v199, 6, v198
	v_xor_b32_e32 v199, 3, v197
	v_lshl_add_u32 v149, v199, 6, v198
	v_lshlrev_b32_e32 v198, 2, v155
	v_add_u32_e32 v150, s9, v198
	v_xor_b32_e32 v199, 64, v198
	v_add_u32_e32 v151, s9, v199
	v_xor_b32_e32 v199, 128, v198
	v_add_u32_e32 v152, s9, v199
	v_xor_b32_e32 v199, 192, v198
	v_add_u32_e32 v153, s9, v199
	v_add_u32_e32 v154, 0x10000, v121
	v_add_u32_e32 v208, s10, v145
	ds_read_b128 v[156:159], v208
	s_waitcnt lgkmcnt(0)
	v_mfma_f32_16x16x4_f32 v[212:215], v156, v160, 0
	v_mfma_f32_16x16x4_f32 v[216:219], v156, v161, 0
	v_mfma_f32_16x16x4_f32 v[220:223], v156, v168, 0
	v_mfma_f32_16x16x4_f32 v[224:227], v156, v169, 0
	v_mfma_f32_16x16x4_f32 v[228:231], v156, v176, 0
	v_mfma_f32_16x16x4_f32 v[232:235], v156, v177, 0
	v_mfma_f32_16x16x4_f32 v[236:239], v156, v184, 0
	v_mfma_f32_16x16x4_f32 v[240:243], v156, v185, 0
	v_mfma_f32_16x16x4_f32 v[212:215], v157, v162, v[212:215]
	v_mfma_f32_16x16x4_f32 v[216:219], v157, v163, v[216:219]
	v_mfma_f32_16x16x4_f32 v[220:223], v157, v170, v[220:223]
	v_mfma_f32_16x16x4_f32 v[224:227], v157, v171, v[224:227]
	v_mfma_f32_16x16x4_f32 v[228:231], v157, v178, v[228:231]
	v_mfma_f32_16x16x4_f32 v[232:235], v157, v179, v[232:235]
	v_mfma_f32_16x16x4_f32 v[236:239], v157, v186, v[236:239]
	v_mfma_f32_16x16x4_f32 v[240:243], v157, v187, v[240:243]
	v_mfma_f32_16x16x4_f32 v[212:215], v158, v164, v[212:215]
	v_mfma_f32_16x16x4_f32 v[216:219], v158, v165, v[216:219]
	v_mfma_f32_16x16x4_f32 v[220:223], v158, v172, v[220:223]
	v_mfma_f32_16x16x4_f32 v[224:227], v158, v173, v[224:227]
	v_mfma_f32_16x16x4_f32 v[228:231], v158, v180, v[228:231]
	v_mfma_f32_16x16x4_f32 v[232:235], v158, v181, v[232:235]
	v_mfma_f32_16x16x4_f32 v[236:239], v158, v188, v[236:239]
	v_mfma_f32_16x16x4_f32 v[240:243], v158, v189, v[240:243]
	v_mfma_f32_16x16x4_f32 v[212:215], v159, v166, v[212:215]
	v_mfma_f32_16x16x4_f32 v[216:219], v159, v167, v[216:219]
	v_mfma_f32_16x16x4_f32 v[220:223], v159, v174, v[220:223]
	v_mfma_f32_16x16x4_f32 v[224:227], v159, v175, v[224:227]
	v_mfma_f32_16x16x4_f32 v[228:231], v159, v182, v[228:231]
	v_mfma_f32_16x16x4_f32 v[232:235], v159, v183, v[232:235]
	v_mfma_f32_16x16x4_f32 v[236:239], v159, v190, v[236:239]
	v_mfma_f32_16x16x4_f32 v[240:243], v159, v191, v[240:243]
	s_branch .LBB0_1051

.LBB0_1051:
	s_nop 9
	s_mov_b32 exec_lo, -1
	s_mov_b32 exec_hi, 0
	ds_write_b32 v146, v212
	ds_write_b32 v146, v213 offset:512
	ds_write_b32 v146, v214 offset:1024
	ds_write_b32 v146, v215 offset:1536
	ds_write_b32 v146, v216 offset:256
	ds_write_b32 v146, v217 offset:768
	ds_write_b32 v146, v218 offset:1280
	ds_write_b32 v146, v219 offset:1792
	ds_write_b32 v147, v220
	ds_write_b32 v147, v221 offset:512
	ds_write_b32 v147, v222 offset:1024
	ds_write_b32 v147, v223 offset:1536
	ds_write_b32 v147, v224 offset:256
	ds_write_b32 v147, v225 offset:768
	ds_write_b32 v147, v226 offset:1280
	ds_write_b32 v147, v227 offset:1792
	ds_write_b32 v148, v228
	ds_write_b32 v148, v229 offset:512
	ds_write_b32 v148, v230 offset:1024
	ds_write_b32 v148, v231 offset:1536
	ds_write_b32 v148, v232 offset:256
	ds_write_b32 v148, v233 offset:768
	ds_write_b32 v148, v234 offset:1280
	ds_write_b32 v148, v235 offset:1792
	ds_write_b32 v149, v236
	ds_write_b32 v149, v237 offset:512
	ds_write_b32 v149, v238 offset:1024
	ds_write_b32 v149, v239 offset:1536
	ds_write_b32 v149, v240 offset:256
	ds_write_b32 v149, v241 offset:768
	ds_write_b32 v149, v242 offset:1280
	ds_write_b32 v149, v243 offset:1792
	s_mov_b64 exec, -1
	ds_read_b32 v196, v150
	ds_read_b32 v197, v150 offset:256
	ds_read_b32 v198, v150 offset:512
	ds_read_b32 v199, v150 offset:768
	ds_read_b32 v200, v150 offset:1024
	ds_read_b32 v201, v150 offset:1280
	ds_read_b32 v202, v150 offset:1536
	ds_read_b32 v203, v150 offset:1792
	ds_read_b32 v244, v151 offset:2048
	ds_read_b32 v245, v151 offset:2304
	ds_read_b32 v246, v151 offset:2560
	ds_read_b32 v247, v151 offset:2816
	ds_read_b32 v248, v151 offset:3072
	ds_read_b32 v249, v151 offset:3328
	ds_read_b32 v250, v151 offset:3584
	ds_read_b32 v251, v151 offset:3840
	s_waitcnt lgkmcnt(8)
	v_pk_fma_f32 v[252:253], v[74:75], v[76:77], v[196:197] op_sel:[0,1,0] op_sel_hi:[1,0,1] neg_lo:[1,0,0] neg_hi:[0,0,0]
	s_nop 0
	v_pk_fma_f32 v[204:205], v[72:73], v[76:77], v[252:253]
	v_pk_fma_f32 v[252:253], v[74:75], v[204:205], v[198:199] op_sel:[0,1,0] op_sel_hi:[1,0,1] neg_lo:[1,0,0] neg_hi:[0,0,0]
	v_bfe_u32 v206, v204, 16, 1
	v_pk_fma_f32 v[76:77], v[72:73], v[204:205], v[252:253]
	v_bfe_u32 v207, v205, 16, 1
	v_add3_u32 v206, v204, v206, s77
	v_add3_u32 v207, v205, v207, s77
	ds_write_b16_d16_hi v154, v206
	ds_write_b16_d16_hi v154, v207 offset:128
	v_pk_fma_f32 v[252:253], v[74:75], v[76:77], v[200:201] op_sel:[0,1,0] op_sel_hi:[1,0,1] neg_lo:[1,0,0] neg_hi:[0,0,0]
	v_bfe_u32 v206, v76, 16, 1
	v_pk_fma_f32 v[204:205], v[72:73], v[76:77], v[252:253]
	v_bfe_u32 v207, v77, 16, 1
	v_add3_u32 v206, v76, v206, s77
	v_add3_u32 v207, v77, v207, s77
	ds_write_b16_d16_hi v154, v206 offset:272
	ds_write_b16_d16_hi v154, v207 offset:400
	v_pk_fma_f32 v[252:253], v[74:75], v[204:205], v[202:203] op_sel:[0,1,0] op_sel_hi:[1,0,1] neg_lo:[1,0,0] neg_hi:[0,0,0]
	v_bfe_u32 v206, v204, 16, 1
	v_pk_fma_f32 v[76:77], v[72:73], v[204:205], v[252:253]
	v_bfe_u32 v207, v205, 16, 1
	v_add3_u32 v206, v204, v206, s77
	v_add3_u32 v207, v205, v207, s77
	ds_write_b16_d16_hi v154, v206 offset:544
	ds_write_b16_d16_hi v154, v207 offset:672
	s_waitcnt lgkmcnt(0)
	v_pk_fma_f32 v[252:253], v[74:75], v[76:77], v[244:245] op_sel:[0,1,0] op_sel_hi:[1,0,1] neg_lo:[1,0,0] neg_hi:[0,0,0]
	v_bfe_u32 v206, v76, 16, 1
	v_pk_fma_f32 v[204:205], v[72:73], v[76:77], v[252:253]
	v_bfe_u32 v207, v77, 16, 1
	v_add3_u32 v206, v76, v206, s77
	v_add3_u32 v207, v77, v207, s77
	ds_write_b16_d16_hi v154, v206 offset:816
	ds_write_b16_d16_hi v154, v207 offset:944
	v_pk_fma_f32 v[252:253], v[74:75], v[204:205], v[246:247] op_sel:[0,1,0] op_sel_hi:[1,0,1] neg_lo:[1,0,0] neg_hi:[0,0,0]
	v_bfe_u32 v206, v204, 16, 1
	v_pk_fma_f32 v[76:77], v[72:73], v[204:205], v[252:253]
	v_bfe_u32 v207, v205, 16, 1
	v_add3_u32 v206, v204, v206, s77
	v_add3_u32 v207, v205, v207, s77
	ds_write_b16_d16_hi v154, v206 offset:1088
	ds_write_b16_d16_hi v154, v207 offset:1216
	v_pk_fma_f32 v[252:253], v[74:75], v[76:77], v[248:249] op_sel:[0,1,0] op_sel_hi:[1,0,1] neg_lo:[1,0,0] neg_hi:[0,0,0]
	v_bfe_u32 v206, v76, 16, 1
	v_pk_fma_f32 v[204:205], v[72:73], v[76:77], v[252:253]
	v_bfe_u32 v207, v77, 16, 1
	v_add3_u32 v206, v76, v206, s77
	v_add3_u32 v207, v77, v207, s77
	ds_write_b16_d16_hi v154, v206 offset:1360
	ds_write_b16_d16_hi v154, v207 offset:1488
	v_pk_fma_f32 v[252:253], v[74:75], v[204:205], v[250:251] op_sel:[0,1,0] op_sel_hi:[1,0,1] neg_lo:[1,0,0] neg_hi:[0,0,0]
	v_bfe_u32 v206, v204, 16, 1
	v_pk_fma_f32 v[76:77], v[72:73], v[204:205], v[252:253]
	v_bfe_u32 v207, v205, 16, 1
	v_add3_u32 v206, v204, v206, s77
	v_add3_u32 v207, v205, v207, s77
	ds_write_b16_d16_hi v154, v206 offset:1632
	ds_write_b16_d16_hi v154, v207 offset:1760
	s_mov_b32 exec_lo, 0
	s_mov_b32 exec_hi, -1
	ds_write_b32 v146, v212
	ds_write_b32 v146, v213 offset:512
	ds_write_b32 v146, v214 offset:1024
	ds_write_b32 v146, v215 offset:1536
	ds_write_b32 v146, v216 offset:256
	ds_write_b32 v146, v217 offset:768
	ds_write_b32 v146, v218 offset:1280
	ds_write_b32 v146, v219 offset:1792
	ds_write_b32 v147, v220
	ds_write_b32 v147, v221 offset:512
	ds_write_b32 v147, v222 offset:1024
	ds_write_b32 v147, v223 offset:1536
	ds_write_b32 v147, v224 offset:256
	ds_write_b32 v147, v225 offset:768
	ds_write_b32 v147, v226 offset:1280
	ds_write_b32 v147, v227 offset:1792
	ds_write_b32 v148, v228
	ds_write_b32 v148, v229 offset:512
	ds_write_b32 v148, v230 offset:1024
	ds_write_b32 v148, v231 offset:1536
	ds_write_b32 v148, v232 offset:256
	ds_write_b32 v148, v233 offset:768
	ds_write_b32 v148, v234 offset:1280
	ds_write_b32 v148, v235 offset:1792
	ds_write_b32 v149, v236
	ds_write_b32 v149, v237 offset:512
	ds_write_b32 v149, v238 offset:1024
	ds_write_b32 v149, v239 offset:1536
	ds_write_b32 v149, v240 offset:256
	ds_write_b32 v149, v241 offset:768
	ds_write_b32 v149, v242 offset:1280
	ds_write_b32 v149, v243 offset:1792
	s_mov_b64 exec, -1
	v_add_u32_e32 v208, s10, v145
	ds_read_b128 v[156:159], v208 offset:16384
	ds_read_b32 v196, v152
	ds_read_b32 v197, v152 offset:256
	ds_read_b32 v198, v152 offset:512
	ds_read_b32 v199, v152 offset:768
	ds_read_b32 v200, v152 offset:1024
	ds_read_b32 v201, v152 offset:1280
	ds_read_b32 v202, v152 offset:1536
	ds_read_b32 v203, v152 offset:1792
	ds_read_b32 v244, v153 offset:2048
	ds_read_b32 v245, v153 offset:2304
	ds_read_b32 v246, v153 offset:2560
	ds_read_b32 v247, v153 offset:2816
	ds_read_b32 v248, v153 offset:3072
	ds_read_b32 v249, v153 offset:3328
	ds_read_b32 v250, v153 offset:3584
	ds_read_b32 v251, v153 offset:3840
	s_cmp_eq_u32 s11, 3
	s_cbranch_scc1 .Ls5p2_nomf_a
	s_waitcnt lgkmcnt(8)
	v_pk_fma_f32 v[252:253], v[74:75], v[76:77], v[196:197] op_sel:[0,1,0] op_sel_hi:[1,0,1] neg_lo:[1,0,0] neg_hi:[0,0,0]
	v_mfma_f32_16x16x4_f32 v[212:215], v156, v160, 0
	v_bfe_u32 v206, v76, 16, 1
	v_pk_fma_f32 v[204:205], v[72:73], v[76:77], v[252:253]
	v_mfma_f32_16x16x4_f32 v[216:219], v156, v161, 0
	v_bfe_u32 v207, v77, 16, 1
	v_add3_u32 v206, v76, v206, s77
	v_add3_u32 v207, v77, v207, s77
	v_mfma_f32_16x16x4_f32 v[220:223], v156, v168, 0
	ds_write_b16_d16_hi v154, v206 offset:1904
	ds_write_b16_d16_hi v154, v207 offset:2032
	v_mfma_f32_16x16x4_f32 v[224:227], v156, v169, 0
	v_pk_fma_f32 v[252:253], v[74:75], v[204:205], v[198:199] op_sel:[0,1,0] op_sel_hi:[1,0,1] neg_lo:[1,0,0] neg_hi:[0,0,0]
	v_mfma_f32_16x16x4_f32 v[228:231], v156, v176, 0
	v_bfe_u32 v206, v204, 16, 1
	v_pk_fma_f32 v[76:77], v[72:73], v[204:205], v[252:253]
	v_mfma_f32_16x16x4_f32 v[232:235], v156, v177, 0
	v_bfe_u32 v207, v205, 16, 1
	v_add3_u32 v206, v204, v206, s77
	v_add3_u32 v207, v205, v207, s77
	v_mfma_f32_16x16x4_f32 v[236:239], v156, v184, 0
	ds_write_b16_d16_hi v154, v206 offset:2176
	ds_write_b16_d16_hi v154, v207 offset:2304
	v_mfma_f32_16x16x4_f32 v[240:243], v156, v185, 0
	v_pk_fma_f32 v[252:253], v[74:75], v[76:77], v[200:201] op_sel:[0,1,0] op_sel_hi:[1,0,1] neg_lo:[1,0,0] neg_hi:[0,0,0]
	v_mfma_f32_16x16x4_f32 v[212:215], v157, v162, v[212:215]
	v_bfe_u32 v206, v76, 16, 1
	v_pk_fma_f32 v[204:205], v[72:73], v[76:77], v[252:253]
	v_mfma_f32_16x16x4_f32 v[216:219], v157, v163, v[216:219]
	v_bfe_u32 v207, v77, 16, 1
	v_add3_u32 v206, v76, v206, s77
	v_add3_u32 v207, v77, v207, s77
	v_mfma_f32_16x16x4_f32 v[220:223], v157, v170, v[220:223]
	ds_write_b16_d16_hi v154, v206 offset:2448
	ds_write_b16_d16_hi v154, v207 offset:2576
	v_mfma_f32_16x16x4_f32 v[224:227], v157, v171, v[224:227]
	v_pk_fma_f32 v[252:253], v[74:75], v[204:205], v[202:203] op_sel:[0,1,0] op_sel_hi:[1,0,1] neg_lo:[1,0,0] neg_hi:[0,0,0]
	v_mfma_f32_16x16x4_f32 v[228:231], v157, v178, v[228:231]
	v_bfe_u32 v206, v204, 16, 1
	v_pk_fma_f32 v[76:77], v[72:73], v[204:205], v[252:253]
	v_mfma_f32_16x16x4_f32 v[232:235], v157, v179, v[232:235]
	v_bfe_u32 v207, v205, 16, 1
	v_add3_u32 v206, v204, v206, s77
	v_add3_u32 v207, v205, v207, s77
	v_mfma_f32_16x16x4_f32 v[236:239], v157, v186, v[236:239]
	ds_write_b16_d16_hi v154, v206 offset:2720
	ds_write_b16_d16_hi v154, v207 offset:2848
	v_mfma_f32_16x16x4_f32 v[240:243], v157, v187, v[240:243]
	s_waitcnt lgkmcnt(0)
	v_pk_fma_f32 v[252:253], v[74:75], v[76:77], v[244:245] op_sel:[0,1,0] op_sel_hi:[1,0,1] neg_lo:[1,0,0] neg_hi:[0,0,0]
	v_mfma_f32_16x16x4_f32 v[212:215], v158, v164, v[212:215]
	v_bfe_u32 v206, v76, 16, 1
	v_pk_fma_f32 v[204:205], v[72:73], v[76:77], v[252:253]
	v_mfma_f32_16x16x4_f32 v[216:219], v158, v165, v[216:219]
	v_bfe_u32 v207, v77, 16, 1
	v_add3_u32 v206, v76, v206, s77
	v_add3_u32 v207, v77, v207, s77
	v_mfma_f32_16x16x4_f32 v[220:223], v158, v172, v[220:223]
	ds_write_b16_d16_hi v154, v206 offset:2992
	ds_write_b16_d16_hi v154, v207 offset:3120
	v_mfma_f32_16x16x4_f32 v[224:227], v158, v173, v[224:227]
	v_pk_fma_f32 v[252:253], v[74:75], v[204:205], v[246:247] op_sel:[0,1,0] op_sel_hi:[1,0,1] neg_lo:[1,0,0] neg_hi:[0,0,0]
	v_mfma_f32_16x16x4_f32 v[228:231], v158, v180, v[228:231]
	v_bfe_u32 v206, v204, 16, 1
	v_pk_fma_f32 v[76:77], v[72:73], v[204:205], v[252:253]
	v_mfma_f32_16x16x4_f32 v[232:235], v158, v181, v[232:235]
	v_bfe_u32 v207, v205, 16, 1
	v_add3_u32 v206, v204, v206, s77
	v_add3_u32 v207, v205, v207, s77
	v_mfma_f32_16x16x4_f32 v[236:239], v158, v188, v[236:239]
	ds_write_b16_d16_hi v154, v206 offset:3264
	ds_write_b16_d16_hi v154, v207 offset:3392
	v_mfma_f32_16x16x4_f32 v[240:243], v158, v189, v[240:243]
	v_pk_fma_f32 v[252:253], v[74:75], v[76:77], v[248:249] op_sel:[0,1,0] op_sel_hi:[1,0,1] neg_lo:[1,0,0] neg_hi:[0,0,0]
	v_mfma_f32_16x16x4_f32 v[212:215], v159, v166, v[212:215]
	v_bfe_u32 v206, v76, 16, 1
	v_pk_fma_f32 v[204:205], v[72:73], v[76:77], v[252:253]
	v_mfma_f32_16x16x4_f32 v[216:219], v159, v167, v[216:219]
	v_bfe_u32 v207, v77, 16, 1
	v_add3_u32 v206, v76, v206, s77
	v_add3_u32 v207, v77, v207, s77
	v_mfma_f32_16x16x4_f32 v[220:223], v159, v174, v[220:223]
	ds_write_b16_d16_hi v154, v206 offset:3536
	ds_write_b16_d16_hi v154, v207 offset:3664
	v_mfma_f32_16x16x4_f32 v[224:227], v159, v175, v[224:227]
	v_pk_fma_f32 v[252:253], v[74:75], v[204:205], v[250:251] op_sel:[0,1,0] op_sel_hi:[1,0,1] neg_lo:[1,0,0] neg_hi:[0,0,0]
	v_mfma_f32_16x16x4_f32 v[228:231], v159, v182, v[228:231]
	v_bfe_u32 v206, v204, 16, 1
	v_pk_fma_f32 v[76:77], v[72:73], v[204:205], v[252:253]
	v_mfma_f32_16x16x4_f32 v[232:235], v159, v183, v[232:235]
	v_bfe_u32 v207, v205, 16, 1
	v_add3_u32 v206, v204, v206, s77
	v_add3_u32 v207, v205, v207, s77
	v_mfma_f32_16x16x4_f32 v[236:239], v159, v190, v[236:239]
	ds_write_b16_d16_hi v154, v206 offset:3808
	ds_write_b16_d16_hi v154, v207 offset:3936
	v_mfma_f32_16x16x4_f32 v[240:243], v159, v191, v[240:243]
	s_branch .Ls5p2_join_a
.Ls5p2_nomf_a:
	s_waitcnt lgkmcnt(8)
	v_pk_fma_f32 v[252:253], v[74:75], v[76:77], v[196:197] op_sel:[0,1,0] op_sel_hi:[1,0,1] neg_lo:[1,0,0] neg_hi:[0,0,0]
	v_bfe_u32 v206, v76, 16, 1
	v_pk_fma_f32 v[204:205], v[72:73], v[76:77], v[252:253]
	v_bfe_u32 v207, v77, 16, 1
	v_add3_u32 v206, v76, v206, s77
	v_add3_u32 v207, v77, v207, s77
	ds_write_b16_d16_hi v154, v206 offset:1904
	ds_write_b16_d16_hi v154, v207 offset:2032
	v_pk_fma_f32 v[252:253], v[74:75], v[204:205], v[198:199] op_sel:[0,1,0] op_sel_hi:[1,0,1] neg_lo:[1,0,0] neg_hi:[0,0,0]
	v_bfe_u32 v206, v204, 16, 1
	v_pk_fma_f32 v[76:77], v[72:73], v[204:205], v[252:253]
	v_bfe_u32 v207, v205, 16, 1
	v_add3_u32 v206, v204, v206, s77
	v_add3_u32 v207, v205, v207, s77
	ds_write_b16_d16_hi v154, v206 offset:2176
	ds_write_b16_d16_hi v154, v207 offset:2304
	v_pk_fma_f32 v[252:253], v[74:75], v[76:77], v[200:201] op_sel:[0,1,0] op_sel_hi:[1,0,1] neg_lo:[1,0,0] neg_hi:[0,0,0]
	v_bfe_u32 v206, v76, 16, 1
	v_pk_fma_f32 v[204:205], v[72:73], v[76:77], v[252:253]
	v_bfe_u32 v207, v77, 16, 1
	v_add3_u32 v206, v76, v206, s77
	v_add3_u32 v207, v77, v207, s77
	ds_write_b16_d16_hi v154, v206 offset:2448
	ds_write_b16_d16_hi v154, v207 offset:2576
	v_pk_fma_f32 v[252:253], v[74:75], v[204:205], v[202:203] op_sel:[0,1,0] op_sel_hi:[1,0,1] neg_lo:[1,0,0] neg_hi:[0,0,0]
	v_bfe_u32 v206, v204, 16, 1
	v_pk_fma_f32 v[76:77], v[72:73], v[204:205], v[252:253]
	v_bfe_u32 v207, v205, 16, 1
	v_add3_u32 v206, v204, v206, s77
	v_add3_u32 v207, v205, v207, s77
	ds_write_b16_d16_hi v154, v206 offset:2720
	ds_write_b16_d16_hi v154, v207 offset:2848
	s_waitcnt lgkmcnt(0)
	v_pk_fma_f32 v[252:253], v[74:75], v[76:77], v[244:245] op_sel:[0,1,0] op_sel_hi:[1,0,1] neg_lo:[1,0,0] neg_hi:[0,0,0]
	v_bfe_u32 v206, v76, 16, 1
	v_pk_fma_f32 v[204:205], v[72:73], v[76:77], v[252:253]
	v_bfe_u32 v207, v77, 16, 1
	v_add3_u32 v206, v76, v206, s77
	v_add3_u32 v207, v77, v207, s77
	ds_write_b16_d16_hi v154, v206 offset:2992
	ds_write_b16_d16_hi v154, v207 offset:3120
	v_pk_fma_f32 v[252:253], v[74:75], v[204:205], v[246:247] op_sel:[0,1,0] op_sel_hi:[1,0,1] neg_lo:[1,0,0] neg_hi:[0,0,0]
	v_bfe_u32 v206, v204, 16, 1
	v_pk_fma_f32 v[76:77], v[72:73], v[204:205], v[252:253]
	v_bfe_u32 v207, v205, 16, 1
	v_add3_u32 v206, v204, v206, s77
	v_add3_u32 v207, v205, v207, s77
	ds_write_b16_d16_hi v154, v206 offset:3264
	ds_write_b16_d16_hi v154, v207 offset:3392
	v_pk_fma_f32 v[252:253], v[74:75], v[76:77], v[248:249] op_sel:[0,1,0] op_sel_hi:[1,0,1] neg_lo:[1,0,0] neg_hi:[0,0,0]
	v_bfe_u32 v206, v76, 16, 1
	v_pk_fma_f32 v[204:205], v[72:73], v[76:77], v[252:253]
	v_bfe_u32 v207, v77, 16, 1
	v_add3_u32 v206, v76, v206, s77
	v_add3_u32 v207, v77, v207, s77
	ds_write_b16_d16_hi v154, v206 offset:3536
	ds_write_b16_d16_hi v154, v207 offset:3664
	v_pk_fma_f32 v[252:253], v[74:75], v[204:205], v[250:251] op_sel:[0,1,0] op_sel_hi:[1,0,1] neg_lo:[1,0,0] neg_hi:[0,0,0]
	v_bfe_u32 v206, v204, 16, 1
	v_pk_fma_f32 v[76:77], v[72:73], v[204:205], v[252:253]
	v_bfe_u32 v207, v205, 16, 1
	v_add3_u32 v206, v204, v206, s77
	v_add3_u32 v207, v205, v207, s77
	ds_write_b16_d16_hi v154, v206 offset:3808
	ds_write_b16_d16_hi v154, v207 offset:3936
.Ls5p2_join_a:
	s_nop 0
	v_bfe_u32 v206, v76, 16, 1
	v_bfe_u32 v207, v77, 16, 1
	v_add3_u32 v206, v76, v206, s77
	v_add3_u32 v207, v77, v207, s77
	ds_write_b16_d16_hi v154, v206 offset:4080
	ds_write_b16_d16_hi v154, v207 offset:4208
	ds_read_b128 v[16:19], v125
	ds_read_b128 v[56:59], v125 offset:64
	ds_read_b128 v[60:63], v125 offset:128
	v_lshl_or_b32 v55, s11, 4, v65
	s_waitcnt lgkmcnt(2)
	v_mfma_f32_16x16x32_bf16 v[16:19], v[16:19], v[0:3], 0
	s_waitcnt lgkmcnt(1)
	v_mfma_f32_16x16x32_bf16 v[16:19], v[56:59], v[4:7], v[16:19]
	ds_read_b128 v[56:59], v125 offset:192
	s_waitcnt lgkmcnt(1)
	v_mfma_f32_16x16x32_bf16 v[16:19], v[60:63], v[8:11], v[16:19]
	v_lshl_add_u32 v60, v55, 10, v54
	ds_read_b32 v60, v60
	s_waitcnt lgkmcnt(1)
	v_mfma_f32_16x16x32_bf16 v[16:19], v[56:59], v[12:15], v[16:19]
	s_waitcnt lgkmcnt(0)
	s_nop 6
	v_fma_f32 v16, v71, v60, v16
	v_mul_f32_e32 v56, 0x3d372713, v16
	v_mul_f32_e32 v56, v16, v56
	v_fma_f32 v56, v16, v56, v16
	v_mul_f32_e32 v56, 0x3f4c422a, v56
	v_cmp_nlt_f32_e64 s[8:9], |v56|, s79
	s_and_saveexec_b64 s[12:13], s[8:9]
	s_xor_b64 s[8:9], exec, s[12:13]
	s_cbranch_execz .LBB0_1055
	v_add_f32_e64 v57, |v56|, |v56|
	v_mul_f32_e32 v58, 0x3fb8aa3b, v57
	v_rndne_f32_e32 v59, v58
	v_sub_f32_e32 v60, v58, v59
	v_fma_f32 v58, v57, s3, -v58
	v_fmac_f32_e32 v58, 0x32a5705f, v57
	v_add_f32_e32 v58, v60, v58
	v_cvt_i32_f32_e32 v59, v59
	v_exp_f32_e32 v58, v58
	v_cmp_ngt_f32_e32 vcc, s33, v57
	v_ldexp_f32 v58, v58, v59
	s_nop 0
	v_cndmask_b32_e32 v58, 0, v58, vcc
	v_cmp_nlt_f32_e32 vcc, s36, v57
	s_nop 1
	v_cndmask_b32_e32 v57, v122, v58, vcc
	v_add_f32_e32 v57, 1.0, v57
	v_rcp_f32_e32 v57, v57
	s_nop 0
	v_fma_f32 v57, v57, -2.0, 1.0
